# s_setprio 3 for the whole GDN scan item (chunk loop + combine), back to 0 at the item end
# speedup vs baseline: 1.0052x; 1.0012x over previous
.LBB0_761:
	s_or_b64 exec, exec, s[38:39]
	s_setprio 0
	s_barrier

.LBB0_791:
	s_ashr_i32 s41, s40, 31
	v_mov_b64_e32 v[2:3], s[40:41]
	v_mad_u64_u32 v[2:3], s[0:1], v170, s84, v[2:3]
	v_mov_b32_e32 v0, v3
	s_movk_i32 s22, 0x80
	v_mad_u64_u32 v[4:5], s[0:1], v171, s84, v[0:1]
	v_cmp_gt_u32_e64 s[38:39], s22, v169
	v_mov_b32_e32 v3, v4
	s_lshl_b32 s12, s13, 6
	v_cndmask_b32_e64 v0, v196, v197, s[38:39]
	v_lshlrev_b64 v[2:3], 3, v[2:3]
	v_or3_b32 v4, v199, s12, v201
	v_lshl_add_u64 v[6:7], s[92:93], 0, v[0:1]
	v_mov_b32_e32 v5, v1
	v_lshl_add_u64 v[14:15], v[4:5], 1, v[6:7]
	v_or_b32_e32 v6, s13, v2
	v_lshlrev_b32_e32 v0, 7, v199
	v_mad_u64_u32 v[4:5], s[42:43], s51, v6, v[0:1]
	v_mul_lo_u32 v7, s51, v3
	v_and_b32_e32 v0, 32, v169
	v_and_b32_e32 v8, 63, v169
	v_add_u32_e32 v5, v7, v5
	v_lshrrev_b32_e32 v0, 1, v0
	v_lshl_add_u64 v[2:3], v[4:5], 0, v[0:1]
	v_lshlrev_b32_e32 v0, 5, v8
	v_lshl_add_u64 v[172:173], s[92:93], 0, v[2:3]
	v_lshl_or_b32 v2, v48, 11, v0
	v_or_b32_e32 v0, 0x1000, v2
	v_mov_b32_e32 v3, v1
	v_mad_u64_u32 v[4:5], s[42:43], s51, v6, v[0:1]
	v_mad_u64_u32 v[2:3], s[42:43], s51, v6, v[2:3]
	v_lshlrev_b32_e32 v202, 2, v200
	v_add_u32_e32 v5, v7, v5
	v_add_u32_e32 v3, v7, v3
	s_mul_hi_i32 s1, s40, s85
	s_mul_i32 s0, s40, s85
	s_mov_b32 s22, 0
	v_or_b32_e32 v203, 1, v202
	v_or_b32_e32 v204, 2, v202
	v_or_b32_e32 v205, 3, v202
	v_or_b32_e32 v206, 8, v202
	v_or_b32_e32 v207, 9, v202
	v_or_b32_e32 v208, 10, v202
	v_or_b32_e32 v209, 11, v202
	v_or_b32_e32 v210, 16, v202
	v_or_b32_e32 v211, 17, v202
	v_or_b32_e32 v212, 18, v202
	v_or_b32_e32 v213, 19, v202
	v_or_b32_e32 v214, 24, v202
	v_or_b32_e32 v215, 25, v202
	v_or_b32_e32 v216, 26, v202
	v_or_b32_e32 v217, 27, v202
	v_or_b32_e32 v218, 32, v202
	v_or_b32_e32 v219, 33, v202
	v_or_b32_e32 v220, 34, v202
	v_or_b32_e32 v221, 35, v202
	v_or_b32_e32 v222, 40, v202
	v_or_b32_e32 v223, 41, v202
	v_or_b32_e32 v224, 42, v202
	v_or_b32_e32 v225, 43, v202
	v_or_b32_e32 v226, 48, v202
	v_or_b32_e32 v227, 49, v202
	v_or_b32_e32 v228, 50, v202
	v_or_b32_e32 v229, 51, v202
	v_or_b32_e32 v230, 56, v202
	v_or_b32_e32 v231, 57, v202
	v_or_b32_e32 v232, 58, v202
	v_or_b32_e32 v233, 59, v202
	v_lshl_add_u64 v[174:175], s[92:93], 0, v[4:5]
	v_lshl_add_u64 v[176:177], s[92:93], 0, v[2:3]
	s_mov_b64 s[42:43], 0
	v_readlane_b32 s23, v248, 26
	s_setprio 3
	s_mov_b64 s[22:23], 0x8000
	s_lshr_b32 s42, s48, 16
	v_readlane_b32 s43, v248, 26
	s_lshl_b32 s43, s43, 6
	s_add_i32 s43, s43, 63
	s_cmp_lg_u64 s[38:39], 0
	s_movk_i32 s14, 0x4000
	s_mov_b32 s15, 0
	s_cbranch_scc1 .Lscan_fwd
	s_mov_b32 s14, 0xffffc000
	s_mov_b32 s15, -1
